# phase 5 balance: cmp2 tiles on the last 32 GEMM blocks, which do one A1 unit fewer; that round moves to the scan blocks
# speedup vs baseline: 1.0041x; 1.0010x over previous
; __global__ void __launch_bounds__(256, 2) mega(Params p, int ph_lo, int ph_hi) {
;     ...
;         const int nb2 = gridDim.x >= 128 ? 64 : 0;
;         const int nvb = gridDim.x - nb2;
;         const int ubeg = (nb2 && (int)gridDim.x - nb2 - 64 > 0) ? A1_EARLY : 0;
;         const int usplit = nb2 ? ubeg + (4096 - ubeg - 3 * nb2) / nvb * nvb : 4096;
;         if ((int)blockIdx.x < nb2) {
;           phaseB2(p, blockIdx.x, smem, B2_S2, 32);
;           phaseA1(p, blockIdx.x, nb2, usplit, 4096, smem);
;         } else {
;           for (int t = blockIdx.x - nb2; t < 32; t += nvb) cmp2_tile(p, l, t >> 4, t & 15, smem);
.LBB0_1:
	s_load_dwordx16 s[4:19], s[0:1], 0x0
	s_load_dwordx8 s[20:27], s[0:1], 0x180
	v_and_b32_e32 v230, 0x3ff, v0
	v_and_b32_e32 v0, 0x3fffffff, v0
	s_movk_i32 s97, 0x1000
	s_waitcnt lgkmcnt(0)
	v_writelane_b32 v250, s4, 2
	s_movk_i32 s33, 0x7f
	s_mov_b32 s96, 0x3e38aa3b
	v_writelane_b32 v250, s5, 3
	v_writelane_b32 v250, s6, 4
	v_writelane_b32 v250, s7, 5
	v_writelane_b32 v250, s8, 6
	v_writelane_b32 v250, s9, 7
	v_writelane_b32 v250, s10, 8
	v_writelane_b32 v250, s11, 9
	v_writelane_b32 v250, s12, 10
	v_writelane_b32 v250, s13, 11
	v_writelane_b32 v250, s14, 12
	v_writelane_b32 v250, s15, 13
	v_writelane_b32 v250, s16, 14
	v_writelane_b32 v250, s17, 15
	v_writelane_b32 v250, s18, 16
	v_writelane_b32 v250, s19, 17
	s_load_dwordx16 s[4:19], s[0:1], 0x40
	v_mov_b32_e32 v227, 0x358637bd
	v_mov_b32_e32 v232, 0x10900
	v_mov_b32_e32 v233, 0x10a00
	v_mov_b32_e32 v247, 0x10910
	s_waitcnt lgkmcnt(0)
	v_writelane_b32 v250, s4, 18
	v_mov_b32_e32 v245, 0x10920
	v_mov_b32_e32 v246, 0x10930
	v_writelane_b32 v250, s5, 19
	v_writelane_b32 v250, s6, 20
	v_writelane_b32 v250, s7, 21
	v_writelane_b32 v250, s8, 22
	v_writelane_b32 v250, s9, 23
	v_writelane_b32 v250, s10, 24
	v_writelane_b32 v250, s11, 25
	v_writelane_b32 v250, s12, 26
	v_writelane_b32 v250, s13, 27
	v_writelane_b32 v250, s14, 28
	v_writelane_b32 v250, s15, 29
	v_writelane_b32 v250, s16, 30
	v_writelane_b32 v250, s17, 31
	v_writelane_b32 v250, s18, 32
	v_writelane_b32 v250, s19, 33
	s_load_dwordx16 s[68:83], s[0:1], 0x80
	s_load_dwordx16 s[36:51], s[0:1], 0xc0
	s_load_dwordx16 s[4:19], s[0:1], 0x100
	v_mov_b32_e32 v224, 0x10940
	v_mov_b32_e32 v225, 0x10950
	v_mov_b32_e32 v248, 0x10960
	v_mov_b32_e32 v226, 0x10970
	s_waitcnt lgkmcnt(0)
	v_writelane_b32 v250, s4, 34
	v_mov_b32_e32 v228, 0x10980
	v_mov_b32_e32 v229, 0x10990
	v_writelane_b32 v250, s5, 35
	v_writelane_b32 v250, s6, 36
	v_writelane_b32 v250, s7, 37
	v_writelane_b32 v250, s8, 38
	v_writelane_b32 v250, s9, 39
	v_writelane_b32 v250, s10, 40
	v_writelane_b32 v250, s11, 41
	v_writelane_b32 v250, s12, 42
	v_writelane_b32 v250, s13, 43
	v_writelane_b32 v250, s14, 44
	v_writelane_b32 v250, s15, 45
	v_writelane_b32 v250, s16, 46
	v_writelane_b32 v250, s17, 47
	v_writelane_b32 v250, s18, 48
	v_writelane_b32 v250, s19, 49
	s_load_dwordx16 s[52:67], s[0:1], 0x140
	s_load_dwordx4 s[4:7], s[0:1], 0x1a0
	s_load_dword s18, s[0:1], 0x1b8
	s_mov_b32 s16, s2
	s_mov_b32 s15, 0
	v_mov_b32_e32 v231, 0x109a0
	s_waitcnt lgkmcnt(0)
	v_writelane_b32 v250, s4, 50
	v_mov_b32_e32 v239, 0x109b0
	v_mov_b32_e32 v240, 0x109c0
	v_writelane_b32 v250, s5, 51
	v_writelane_b32 v250, s6, 52
	v_writelane_b32 v250, s7, 53
	s_add_u32 s4, s0, 0x1b8
	s_addc_u32 s5, s1, 0
	v_writelane_b32 v250, s4, 54
	s_lshr_b32 s0, s2, 3
	s_cmpk_lt_u32 s2, 0x1000
	v_writelane_b32 v250, s5, 55
	v_writelane_b32 v250, s0, 56
	s_cselect_b64 s[0:1], -1, 0
	v_writelane_b32 v250, s0, 57
	s_lshl_b32 s94, s18, 2
	v_mov_b32_e32 v241, 0x109d0
	v_writelane_b32 v250, s1, 58
	s_lshl_b32 s0, s2, 9
	s_and_b32 s0, s0, 0xe00
	v_writelane_b32 v250, s0, 59
	s_lshr_b32 s0, s18, 3
	v_writelane_b32 v250, s0, 60
	s_lshl_b32 s0, s2, 2
	v_writelane_b32 v250, s0, 61
	s_lshr_b32 s0, s18, 1
	s_sub_i32 s0, s2, s0
	s_lshl_b32 s1, s0, 2
	s_cmp_gt_i32 s0, -1
	v_writelane_b32 v250, s1, 62
	s_cselect_b64 s[0:1], -1, 0
	v_writelane_b32 v250, s0, 63
	v_mov_b32_e32 v242, 0x109e0
	v_mov_b32_e32 v243, 0x109f0
	v_writelane_b32 v251, s1, 0
	s_lshl_b32 s0, s18, 1
	s_and_b32 s0, s0, -4
	s_cmpk_lt_u32 s2, 0x800
	v_writelane_b32 v251, s0, 1
	s_cselect_b64 s[0:1], -1, 0
	v_writelane_b32 v251, s0, 2
	v_mov_b32_e32 v234, 0x7f
	v_mov_b32_e32 v235, 0xf149f2ca
	v_writelane_b32 v251, s1, 3
	s_lshl_b32 s0, s2, 8
	s_and_b32 s0, s0, 0x700
	s_cmpk_lt_u32 s18, 0x80
	s_cselect_b64 s[4:5], -1, 0
	s_cmpk_gt_u32 s18, 0x7f
	s_cselect_b64 s[2:3], -1, 0
	v_writelane_b32 v251, s0, 4
	s_and_b64 s[0:1], s[2:3], exec
	s_cselect_b32 s19, 64, 0
	s_cselect_b32 s11, 0xffffffc0, 0
	s_sub_i32 s14, s18, s19
	s_cmp_gt_i32 s14, 64
	s_cselect_b64 s[0:1], -1, 0
	v_writelane_b32 v251, s2, 5
	s_and_b64 s[8:9], s[2:3], s[0:1]
	s_and_b64 s[0:1], s[8:9], exec
	v_writelane_b32 v251, s3, 6
	s_cselect_b32 s3, 0x300, 0
	s_abs_i32 s2, s14
	v_cvt_f32_u32_e32 v1, s2
	s_mul_i32 s10, s19, -3
	s_sub_i32 s6, 0, s2
	s_sub_i32 s0, s10, s3
	v_rcp_iflag_f32_e32 v1, v1
	s_addk_i32 s0, 0x1000
	s_ashr_i32 s1, s0, 31
	s_abs_i32 s0, s0
	v_mul_f32_e32 v1, 0x4f7ffffe, v1
	v_cvt_u32_f32_e32 v1, v1
	v_mov_b32_e32 v236, 0x4e6e6b28
	v_mov_b32_e32 v237, 0x10800
	v_mov_b32_e32 v238, 0xd00
	v_readfirstlane_b32 s7, v1
	s_mul_i32 s6, s6, s7
	s_mul_hi_u32 s6, s7, s6
	s_add_i32 s7, s7, s6
	s_mul_hi_u32 s6, s0, s7
	s_mul_i32 s6, s6, s2
	s_sub_i32 s0, s0, s6
	s_sub_i32 s6, s0, s2
	s_cmp_ge_u32 s0, s2
	s_cselect_b32 s0, s6, s0
	s_sub_i32 s6, s0, s2
	s_cmp_ge_u32 s0, s2
	s_cselect_b32 s0, s6, s0
	s_xor_b32 s0, s0, s1
	s_sub_i32 s0, s1, s0
	s_add_i32 s10, s10, s0
	s_addk_i32 s10, 0xffe0
	s_cmp_ge_i32 s16, s19
	s_cselect_b64 s[0:1], -1, 0
	s_sub_i32 s28, s16, s19
	v_writelane_b32 v251, s0, 7
	s_add_i32 s2, s28, 32
	s_cmp_ge_i32 s2, s14
	v_mov_b32_e32 v1, 0
	v_writelane_b32 v251, s1, 8
	s_cselect_b64 s[0:1], -1, 0
	v_writelane_b32 v251, s0, 9
	s_ashr_i32 s17, s16, 31
	s_ashr_i32 s2, s16, 2
	v_writelane_b32 v251, s1, 10
	s_add_i32 s0, s3, s28
	v_writelane_b32 v251, s0, 11
	s_and_b32 s29, s16, 3
	s_lshl_b64 s[0:1], s[16:17], 16
	s_add_u32 s0, s60, s0
	s_addc_u32 s1, s61, s1
	v_writelane_b32 v251, s0, 12
	v_mov_b32_e32 v244, 0x10804
	s_nop 0
	v_writelane_b32 v251, s1, 13
	s_lshl_b32 s0, s2, 5
	v_writelane_b32 v251, s0, 14
	s_lshl_b32 s0, s2, 7
	s_or_b32 s0, s0, s29
	s_or_b32 s6, s0, 0x60
	s_ashr_i32 s7, s6, 31
; __global__ void __launch_bounds__(256, 2) mega(Params p, int ph_lo, int ph_hi) {
;     ...
;       case 4: if (PHASE_ONLY >= 0 && PHASE_ONLY != 4) break; {
;         const int nb2 = gridDim.x >= 128 ? 64 : 0;
;         if ((int)blockIdx.x < nb2) phaseB2(p, blockIdx.x, smem, B2_S1, B2_S2);
;         else {
;           for (int t = blockIdx.x - nb2; t < 64 + 1024; t += gridDim.x - nb2) {
;             if (t < 64) cmp1_tile(p, t >> 5, (t >> 1) & 15, t & 1, smem);
;             else { const int tt = t - 64; kvup_tile(p, l, tt >> 2, tt & 3, smem); }
;           }
;           const int va = (int)blockIdx.x - nb2 - 64, nva = (int)gridDim.x - nb2 - 64;
;           if (nb2 && va >= 0 && nva > 0) phaseA1(p, va, nva, 0, A1_EARLY, smem);
	s_lshl_b64 s[12:13], s[6:7], 13
	s_lshl_b64 s[6:7], s[6:7], 14
	s_add_u32 s30, s62, s6
	s_addc_u32 s31, s63, s7
	v_writelane_b32 v251, s30, 15
	s_nop 1
	v_writelane_b32 v251, s31, 16
	s_add_u32 s30, s64, s6
	s_addc_u32 s31, s65, s7
	v_writelane_b32 v251, s30, 17
	s_nop 1
	v_writelane_b32 v251, s31, 18
	s_add_u32 s30, s66, s6
	s_addc_u32 s31, s67, s7
	v_writelane_b32 v251, s30, 19
	s_add_u32 s12, s20, s12
	s_addc_u32 s13, s21, s13
	v_writelane_b32 v251, s31, 20
	v_writelane_b32 v251, s12, 21
	s_add_u32 s6, s22, s6
	s_addc_u32 s7, s23, s7
	v_writelane_b32 v251, s13, 22
	s_lshl_b32 s2, s2, 11
	v_writelane_b32 v251, s6, 23
	s_cmp_lt_i32 s16, 64
	s_nop 0
	v_writelane_b32 v251, s7, 24
	s_cselect_b64 s[6:7], -1, 0
	s_cmpk_lt_i32 s28, 0x440
	s_cselect_b64 s[12:13], -1, 0
	v_writelane_b32 v251, s12, 25
	s_cmp_lg_u64 s[40:41], 0
	s_nop 0
	v_writelane_b32 v251, s13, 26
	s_cselect_b64 s[12:13], -1, 0
	s_add_i32 s1, s11, s18
	v_writelane_b32 v251, s12, 27
	s_cmp_gt_i32 s28, 63
	s_nop 0
	v_writelane_b32 v251, s13, 28
	s_cselect_b64 s[12:13], -1, 0
	v_writelane_b32 v251, s1, 29
	s_and_b64 s[8:9], s[8:9], s[12:13]
	v_writelane_b32 v251, s8, 30
	s_sub_i32 s1, s14, 64
	s_nop 0
	v_writelane_b32 v251, s9, 31
	v_writelane_b32 v251, s1, 32
	s_sub_i32 s1, s28, 64
	s_cmpk_lt_u32 s1, 0x300
	v_writelane_b32 v251, s1, 33
	s_cselect_b64 s[8:9], -1, 0
	v_writelane_b32 v251, s8, 34
	s_nop 1
	v_writelane_b32 v251, s9, 35
	s_or_b32 s8, s0, 0x4c
	s_ashr_i32 s9, s8, 31
	s_lshl_b64 s[12:13], s[8:9], 13
	s_lshl_b64 s[8:9], s[8:9], 14
	s_add_u32 s30, s62, s8
	s_addc_u32 s31, s63, s9
	v_writelane_b32 v251, s30, 36
	s_nop 1
	v_writelane_b32 v251, s31, 37
	s_add_u32 s30, s64, s8
	s_addc_u32 s31, s65, s9
	v_writelane_b32 v251, s30, 38
	s_nop 1
	v_writelane_b32 v251, s31, 39
	s_add_u32 s30, s66, s8
	s_addc_u32 s31, s67, s9
	v_writelane_b32 v251, s30, 40
	s_add_u32 s12, s20, s12
	s_addc_u32 s13, s21, s13
	v_writelane_b32 v251, s31, 41
	v_writelane_b32 v251, s12, 42
	s_add_u32 s8, s22, s8
	s_addc_u32 s9, s23, s9
	v_writelane_b32 v251, s13, 43
	v_writelane_b32 v251, s8, 44
	s_cmpk_lt_u32 s28, 0x1400
	s_nop 0
	v_writelane_b32 v251, s9, 45
	s_cselect_b64 s[8:9], -1, 0
	v_writelane_b32 v251, s8, 46
	s_lshr_b32 s1, s28, 3
	s_and_b32 s11, s16, 7
	v_writelane_b32 v251, s9, 47
	v_writelane_b32 v251, s28, 48
	v_writelane_b32 v251, s1, 49
	s_mul_i32 s1, s11, 0x280
	v_writelane_b32 v251, s1, 50
	v_writelane_b32 v251, s14, 51
	s_ashr_i32 s1, s14, 3
	v_writelane_b32 v251, s1, 52
	s_ashr_i32 s1, s0, 31
	s_lshl_b64 s[8:9], s[0:1], 13
	s_lshl_b64 s[12:13], s[0:1], 14
	s_add_u32 s30, s62, s12
	s_addc_u32 s31, s63, s13
	v_writelane_b32 v251, s30, 53
	s_nop 1
	v_writelane_b32 v251, s31, 54
	s_add_u32 s30, s64, s12
	s_addc_u32 s31, s65, s13
	v_writelane_b32 v251, s30, 55
	s_nop 1
	v_writelane_b32 v251, s31, 56
	s_add_u32 s30, s66, s12
	s_addc_u32 s31, s67, s13
	v_writelane_b32 v251, s30, 57
	s_add_u32 s8, s20, s8
	s_addc_u32 s9, s21, s9
	v_writelane_b32 v251, s31, 58
	v_writelane_b32 v251, s8, 59
	s_nop 1
	v_writelane_b32 v251, s9, 60
	s_add_u32 s8, s22, s12
	s_addc_u32 s9, s23, s13
	v_writelane_b32 v251, s8, 61
	s_cmpk_lt_i32 s16, 0x800
	s_nop 0
	v_writelane_b32 v251, s9, 62
	s_cselect_b64 s[8:9], -1, 0
	s_ashr_i32 s1, s16, 3
	v_writelane_b32 v251, s8, 63
	s_cmpk_lt_i32 s1, 0x1a0
	s_nop 0
	v_writelane_b32 v252, s9, 0
	v_writelane_b32 v252, s1, 1
	s_cselect_b64 s[8:9], -1, 0
	v_writelane_b32 v252, s8, 2
	s_mul_i32 s1, s11, 0x1a0
	s_add_i32 s11, s16, 0xe0
	v_writelane_b32 v252, s9, 3
	v_writelane_b32 v252, s1, 4
	s_ashr_i32 s1, s18, 3
	v_writelane_b32 v252, s1, 5
	s_add_i32 s1, s18, -1
	v_writelane_b32 v252, s1, 6
	s_add_i32 s1, s16, 64
	s_add_i32 s8, s16, 0x60
	s_add_i32 s9, s16, 0x50
	s_add_u32 s12, s80, 0x100000
	s_addc_u32 s13, s81, 0
	v_writelane_b32 v252, s12, 7
	s_nop 1
	v_writelane_b32 v252, s13, 8
	s_add_i32 s12, s16, 0x58
	s_add_u32 s30, s82, 0x10000
	v_writelane_b32 v252, s68, 9
	s_addc_u32 s31, s83, 0
	s_and_b64 s[4:5], s[4:5], s[6:7]
	v_writelane_b32 v252, s69, 10
	v_writelane_b32 v252, s70, 11
	v_writelane_b32 v252, s71, 12
	v_writelane_b32 v252, s72, 13
	v_writelane_b32 v252, s73, 14
	v_writelane_b32 v252, s74, 15
	v_writelane_b32 v252, s75, 16
	v_writelane_b32 v252, s76, 17
	v_writelane_b32 v252, s77, 18
	v_writelane_b32 v252, s78, 19
	v_writelane_b32 v252, s79, 20
	v_writelane_b32 v252, s80, 21
	v_writelane_b32 v252, s81, 22
	v_writelane_b32 v252, s82, 23
	v_writelane_b32 v252, s83, 24
	v_writelane_b32 v252, s30, 25
	s_add_i32 s13, s16, 0x160
	s_add_i32 s14, s16, 0xc8
	v_writelane_b32 v252, s31, 26
	v_cmp_eq_u32_e64 s[30:31], 0, v0
	v_cvt_f32_u32_e32 v0, s18
	s_movk_i32 s76, 0x90
	v_writelane_b32 v252, s30, 27
	s_movk_i32 s77, 0x200
	v_rcp_iflag_f32_e32 v0, v0
	v_writelane_b32 v252, s31, 28
	v_writelane_b32 v252, s4, 29
	s_movk_i32 s79, 0x210
	v_mul_f32_e32 v0, 0x4f7ffffe, v0
	v_cvt_u32_f32_e32 v0, v0
	v_writelane_b32 v252, s5, 30
	s_add_i32 s4, s10, 0x1000
	v_writelane_b32 v252, s4, 31
	s_sub_i32 s4, 0, s18
	v_readfirstlane_b32 s5, v0
	s_mul_i32 s4, s4, s5
	s_mul_hi_u32 s4, s5, s4
	s_add_i32 s5, s5, s4
	s_mul_hi_u32 s4, s16, s5
	s_mul_i32 s4, s4, s18
	s_sub_i32 s4, s16, s4
	s_sub_i32 s6, s4, s18
	s_cmp_ge_u32 s4, s18
	s_cselect_b32 s4, s6, s4
	s_sub_i32 s6, s4, s18
	s_cmp_ge_u32 s4, s18
	s_cselect_b32 s4, s6, s4
	v_writelane_b32 v252, s4, 32
	s_cmpk_lt_i32 s4, 0x720
	s_mul_hi_u32 s4, s1, s5
	s_mul_i32 s4, s4, s18
	s_cselect_b64 s[6:7], -1, 0
	s_sub_i32 s1, s1, s4
	s_sub_i32 s4, s1, s18
	s_cmp_ge_u32 s1, s18
	s_cselect_b32 s1, s4, s1
	s_sub_i32 s4, s1, s18
	v_writelane_b32 v252, s6, 33
	s_cmp_ge_u32 s1, s18
	s_cselect_b32 s1, s4, s1
	v_writelane_b32 v252, s7, 34
	v_writelane_b32 v252, s1, 35
; #define TIDX (tid_launder())
; DI void tr_job(const float* __restrict__ src, int ld, int K, int Nsrc, bool map, bf16_t* __restrict__ dst, int Nrows,
;                float* lds, int rot) {
;   const int ntk = K / 64, ntiles = (Nrows / 64) * ntk;
;   const int vb = (blockIdx.x + rot) % gridDim.x;
;   const int tx = TIDX & 63, ty = TIDX >> 6;
;   for (int t = vb; t < ntiles; t += gridDim.x) {
; DI void phase0(const Params& p, int l, char* smem) {
;   float* lds = (float*)smem;
;   if (l == 0 && blockIdx.x == gridDim.x - 1) build_lut(p, p.lutg);
;   tr_job(p.w_in + (size_t)l * 1024 * 7260, 7260, 1024, 7260, true, p.wt_in, 7296, lds, 0);
;   tr_job(p.a_w_ukv + (size_t)l * 128 * 512, 512, 128, 512, false, p.wt_ukv, 512, lds, 64);
;   for (int kv = 0; kv < 2; ++kv) {
;     tr_job(p.c_phi_w1 + ((size_t)l * 2 + kv) * 2048 * 256, 256, 2048, 256, false, p.wt_phi1 + (size_t)kv * 256 * 2048, 256, lds, 96 + kv * 128);
;     tr_job(p.c_phi_w2 + ((size_t)l * 2 + kv) * 256 * 64, 64, 256, 64, false, p.wt_phi2 + (size_t)kv * 128 * 256, 128, lds, 80 + kv * 8);
;   }
;   tr_job(p.w_branch + (size_t)l * 1024 * 1024, 1024, 1024, 1024, false, p.wt_br, 1024, lds, 352);
;   tr_job(p.w_out + (size_t)l * 1024 * 1024, 1024, 1024, 1024, false, p.wt_out, 1024, lds, 96);
;   {
;     const int vb = (blockIdx.x + 200) % gridDim.x;
;     for (int j = vb; j < 16; j += gridDim.x) {
	s_cmp_lt_i32 s1, 16
	s_mul_hi_u32 s1, s8, s5
	s_mul_i32 s1, s1, s18
	s_cselect_b64 s[6:7], -1, 0
	s_sub_i32 s1, s8, s1
	s_sub_i32 s4, s1, s18
	s_cmp_ge_u32 s1, s18
	s_cselect_b32 s1, s4, s1
	s_sub_i32 s4, s1, s18
	v_writelane_b32 v252, s6, 36
	s_cmp_ge_u32 s1, s18
	v_mbcnt_lo_u32_b32 v0, -1, 0
	v_writelane_b32 v252, s7, 37
	s_cselect_b32 s6, s4, s1
	s_mul_hi_u32 s1, s9, s5
	s_cmpk_lt_i32 s6, 0x80
	s_mul_i32 s1, s1, s18
	s_cselect_b64 s[30:31], -1, 0
	s_sub_i32 s1, s9, s1
	s_sub_i32 s4, s1, s18
	s_cmp_ge_u32 s1, s18
	s_cselect_b32 s1, s4, s1
	s_sub_i32 s4, s1, s18
	v_writelane_b32 v252, s30, 38
	s_cmp_ge_u32 s1, s18
	s_cselect_b32 s1, s4, s1
	v_writelane_b32 v252, s31, 39
	v_writelane_b32 v252, s1, 40
	s_cmp_lt_i32 s1, 8
	s_mul_hi_u32 s1, s11, s5
	s_mul_i32 s1, s1, s18
	s_cselect_b64 s[8:9], -1, 0
	s_sub_i32 s1, s11, s1
	s_sub_i32 s4, s1, s18
	s_cmp_ge_u32 s1, s18
	s_cselect_b32 s1, s4, s1
	s_sub_i32 s4, s1, s18
	v_writelane_b32 v252, s8, 41
	s_cmp_ge_u32 s1, s18
	s_cselect_b32 s1, s4, s1
	v_writelane_b32 v252, s9, 42
	v_writelane_b32 v252, s1, 43
	s_cmpk_lt_i32 s1, 0x80
	s_mul_hi_u32 s1, s12, s5
	s_mul_i32 s1, s1, s18
	s_cselect_b64 s[8:9], -1, 0
	s_sub_i32 s1, s12, s1
	s_sub_i32 s4, s1, s18
	s_cmp_ge_u32 s1, s18
	s_cselect_b32 s1, s4, s1
	s_sub_i32 s4, s1, s18
	v_writelane_b32 v252, s8, 44
	s_cmp_ge_u32 s1, s18
	s_cselect_b32 s1, s4, s1
	v_writelane_b32 v252, s9, 45
	v_writelane_b32 v252, s1, 46
	s_cmp_lt_i32 s1, 8
	s_mul_hi_u32 s1, s13, s5
	s_mul_i32 s1, s1, s18
	s_cselect_b64 s[8:9], -1, 0
	s_sub_i32 s1, s13, s1
	s_sub_i32 s4, s1, s18
	s_cmp_ge_u32 s1, s18
	s_cselect_b32 s1, s4, s1
	s_sub_i32 s4, s1, s18
	s_cmp_ge_u32 s1, s18
	v_writelane_b32 v252, s8, 47
	s_cselect_b32 s1, s4, s1
	s_cmpk_lt_i32 s1, 0x100
	v_writelane_b32 v252, s9, 48
	v_writelane_b32 v252, s1, 49
	s_cselect_b64 s[8:9], -1, 0
	v_writelane_b32 v252, s8, 50
	s_mul_hi_u32 s1, s14, s5
	s_cmpk_lt_i32 s6, 0x100
	v_writelane_b32 v252, s9, 51
	s_mul_i32 s1, s1, s18
	v_writelane_b32 v252, s6, 52
	s_cselect_b64 s[6:7], -1, 0
	s_sub_i32 s1, s14, s1
	s_sub_i32 s4, s1, s18
	s_cmp_ge_u32 s1, s18
	s_cselect_b32 s1, s4, s1
	s_sub_i32 s4, s1, s18
	s_cmp_ge_u32 s1, s18
	s_cselect_b32 s4, s4, s1
	v_writelane_b32 v252, s6, 53
	s_cmp_lt_i32 s4, 16
	s_mov_b32 s82, 0xf149f2ca
	v_writelane_b32 v252, s7, 54
	s_cselect_b64 s[6:7], -1, 0
	v_writelane_b32 v252, s6, 55
	s_movk_i32 s80, 0x2000
	s_movk_i32 s81, 0x3000
	v_writelane_b32 v252, s7, 56
	s_add_u32 s6, s48, 0x200
	v_writelane_b32 v252, s36, 57
	s_addc_u32 s7, s49, 0
	s_ashr_i32 s95, s94, 31
	v_writelane_b32 v253, s43, 0
	v_writelane_b32 v253, s44, 1
	v_writelane_b32 v253, s45, 2
	v_writelane_b32 v253, s46, 3
	v_writelane_b32 v253, s47, 4
	v_writelane_b32 v253, s48, 5
	v_writelane_b32 v253, s49, 6
	v_writelane_b32 v253, s50, 7
	v_writelane_b32 v253, s51, 8
	v_writelane_b32 v253, s6, 9
	s_lshl_b64 s[44:45], s[94:95], 11
	v_writelane_b32 v252, s37, 58
	v_writelane_b32 v253, s7, 10
	s_add_u32 s6, s54, 0xc00
	v_writelane_b32 v253, s52, 11
	s_addc_u32 s7, s55, 0
	s_sub_i32 s1, s19, s3
	v_writelane_b32 v253, s53, 12
	v_writelane_b32 v253, s54, 13
	v_writelane_b32 v253, s55, 14
	v_writelane_b32 v253, s56, 15
	v_writelane_b32 v253, s57, 16
	v_writelane_b32 v253, s58, 17
	v_writelane_b32 v253, s59, 18
	v_writelane_b32 v253, s60, 19
	v_writelane_b32 v253, s61, 20
	v_writelane_b32 v253, s62, 21
	v_writelane_b32 v253, s63, 22
	v_writelane_b32 v253, s64, 23
	v_writelane_b32 v253, s65, 24
	v_writelane_b32 v253, s66, 25
	v_writelane_b32 v253, s67, 26
	v_writelane_b32 v253, s6, 27
	s_sub_i32 s1, s1, s16
	s_addk_i32 s1, 0xfff
	v_writelane_b32 v253, s7, 28
	s_ashr_i32 s3, s2, 31
	v_writelane_b32 v253, s1, 29
	s_lshl_b64 s[2:3], s[2:3], 10
	s_lshl_b32 s1, s29, 8
	s_sub_i32 s5, s19, s18
	s_or_b32 s1, s2, s1
	s_add_u32 s2, s26, s1
	s_addc_u32 s3, s27, s3
	s_add_u32 s6, s2, 0x180000
	v_writelane_b32 v253, s2, 30
	s_addc_u32 s7, s3, 0
	v_readlane_b32 s52, v250, 18
	v_writelane_b32 v253, s3, 31
	v_writelane_b32 v253, s6, 32
	s_add_u32 s2, s26, 0x180000
	v_readlane_b32 s64, v250, 30
	v_writelane_b32 v253, s7, 33
	v_writelane_b32 v253, s20, 34
	s_addc_u32 s3, s27, 0
	s_sub_i32 s1, s19, s16
	v_writelane_b32 v253, s21, 35
	v_writelane_b32 v253, s22, 36
	v_writelane_b32 v253, s23, 37
	v_writelane_b32 v253, s24, 38
	v_writelane_b32 v253, s25, 39
	v_writelane_b32 v253, s26, 40
	v_writelane_b32 v253, s27, 41
	v_writelane_b32 v253, s2, 42
	s_addk_i32 s1, 0x103f
	v_readlane_b32 s65, v250, 31
	v_writelane_b32 v253, s3, 43
	s_mov_b32 s2, s16
	v_writelane_b32 v253, s2, 44
	v_readlane_b32 s62, v250, 28
	v_readlane_b32 s63, v250, 29
	v_writelane_b32 v253, s3, 45
	v_writelane_b32 v253, s19, 46
	v_writelane_b32 v253, s1, 47
	v_writelane_b32 v253, s5, 48
	s_add_i32 s1, s5, 64
	v_writelane_b32 v253, s1, 49
	s_or_b32 s1, s0, 0x50
	v_writelane_b32 v253, s1, 50
	s_or_b32 s0, s0, 4
	v_writelane_b32 v253, s0, 51
	s_add_u32 s0, s64, 0x7c00
	v_writelane_b32 v253, s0, 52
	s_addc_u32 s0, s65, 0
	v_writelane_b32 v253, s0, 53
	v_writelane_b32 v253, s4, 54
	s_lshl_b32 s0, s4, 5
	v_writelane_b32 v253, s0, 55
	v_writelane_b32 v253, s18, 56
	s_lshl_b32 s0, s18, 5
	v_writelane_b32 v253, s0, 57
	s_add_u32 s0, s62, 0x7c
	v_writelane_b32 v252, s38, 59
	v_writelane_b32 v253, s0, 58
	s_addc_u32 s0, s63, 0
	v_writelane_b32 v252, s39, 60
	v_writelane_b32 v253, s0, 59
	v_writelane_b32 v252, s40, 61
	v_writelane_b32 v253, s29, 60
	v_writelane_b32 v252, s41, 62
	v_writelane_b32 v253, s44, 61
	v_writelane_b32 v252, s42, 63
	s_movk_i32 s42, 0x100
	s_mov_b64 s[40:41], 0x10000
	s_movk_i32 s37, 0x80
	s_movk_i32 s43, 0xfff
	s_movk_i32 s46, 0x7fff
	s_mov_b32 s47, 0xfffffc0
	s_mov_b64 s[48:49], 0x8000
	s_movk_i32 s50, 0xd00
	s_mov_b32 s51, 0x8000
	s_movk_i32 s83, 0x1eff
	s_movk_i32 s95, 0x4000
	v_mbcnt_hi_u32_b32 v249, -1, v0
	v_writelane_b32 v253, s45, 62
	v_readlane_b32 s53, v250, 19
	v_readlane_b32 s54, v250, 20
	v_readlane_b32 s55, v250, 21
	v_readlane_b32 s56, v250, 22
	v_readlane_b32 s57, v250, 23
	v_readlane_b32 s58, v250, 24
	v_readlane_b32 s59, v250, 25
	v_readlane_b32 s60, v250, 26
	v_readlane_b32 s61, v250, 27
	v_readlane_b32 s66, v250, 32
	v_readlane_b32 s67, v250, 33
	s_branch .LBB0_5

; __global__ void __launch_bounds__(256, 2) mega(Params p, int ph_lo, int ph_hi) {
;     ...
;         if ((int)blockIdx.x < nb2) {
;           phaseB2(p, blockIdx.x, smem, B2_S2, 32);
;           phaseA1(p, blockIdx.x, nb2, usplit, 4096, smem);
;         } else {
;           for (int t = blockIdx.x - nb2; t < 32; t += nvb) cmp2_tile(p, l, t >> 4, t & 15, smem);
.LBB0_338:
	v_readlane_b32 s2, v251, 7
	v_readlane_b32 s3, v251, 8
	s_mov_b64 s[0:1], -1
	s_and_b64 vcc, exec, s[2:3]
	s_cbranch_vccz .LBB0_796
	v_readlane_b32 s0, v251, 9
	v_readlane_b32 s1, v251, 10
	s_andn2_b64 vcc, exec, s[0:1]
	v_readlane_b32 s10, v251, 48
	v_readlane_b32 s14, v251, 51
	s_sub_i32 s10, s10, s14
	s_add_i32 s10, s10, 32
	s_mov_b32 s14, 0x800000
	s_movk_i32 s34, 0x7e
	s_movk_i32 s35, 0x7f0
	s_movk_i32 s36, 0xf8
	s_mov_b32 s50, 0x81020409
	s_cbranch_vccz .LBB0_778
